# next-tile stage-0 LDS-DMA prefetch issued before the peeled last K-step in gemmA and gate phases (prologue DMAs skipped when prefetched)
# speedup vs baseline: 1.0777x; 1.0049x over previous
.LBB0_190:
	s_or_b64 exec, exec, s[0:1]
	v_readlane_b32 s16, v215, 6
	s_mov_b64 s[0:1], 0
	v_readlane_b32 s30, v215, 20
	s_barrier
	v_readlane_b32 s31, v215, 21
	s_add_u32 s60, s30, s0
	v_readlane_b32 s28, v215, 18
	s_addc_u32 s62, s31, s1
	s_lshl_b64 s[0:1], s[0:1], 2
	v_readlane_b32 s29, v215, 19
	s_add_u32 s0, s28, s0
	s_addc_u32 s1, s29, s1
	s_add_u32 s64, s60, 0x17fc000
	s_addc_u32 s86, s62, 0
	v_readlane_b32 s4, v215, 25
	s_bitcmp0_b32 s4, 0
	s_cselect_b64 s[2:3], -1, 0
	v_readlane_b32 s17, v215, 7
	v_readlane_b32 s18, v215, 8
	v_readlane_b32 s19, v215, 9
	v_readlane_b32 s20, v215, 10
	v_readlane_b32 s21, v215, 11
	v_readlane_b32 s22, v215, 12
	v_readlane_b32 s23, v215, 13
	v_readlane_b32 s24, v215, 14
	v_readlane_b32 s25, v215, 15
	v_readlane_b32 s26, v215, 16
	v_readlane_b32 s27, v215, 17
	v_readlane_b32 s5, v215, 26
	v_writelane_b32 v215, s2, 29
	s_mov_b32 s92, 0
	s_mov_b32 s100, 0
	s_nop 0
	v_writelane_b32 v215, s3, 30
	s_and_b64 s[2:3], s[2:3], exec
	s_cselect_b32 s2, 0, 0x1db60000
	s_add_u32 s93, s60, s2
	s_addc_u32 s20, s62, 0
	s_lshl_b64 s[6:7], s[4:5], 8
	s_add_u32 s36, s0, 0xa200000
	s_addc_u32 s37, s1, 0
	s_add_u32 s38, s60, 0xd81c000
	s_addc_u32 s21, s62, 0
	s_add_u32 s10, s0, 0xa000000
	s_addc_u32 s11, s1, 0
	s_add_u32 s40, s60, 0xd5fc000
	s_addc_u32 s41, s62, 0
	s_add_u32 s18, s60, 0xc2fc000
	s_addc_u32 s19, s62, 0
	s_add_u32 s42, s60, 0xa7fc000
	s_addc_u32 s43, s62, 0
	s_add_u32 s22, s60, 0x5ffc000
	s_addc_u32 s23, s62, 0
	v_writelane_b32 v215, s2, 31
	s_branch .LBB0_193

.LBB0_193:
	s_add_i32 s2, s92, s85
	s_cmpk_gt_i32 s2, 0x167f
	s_cbranch_scc1 .LBB0_192
	s_ashr_i32 s3, s2, 5
	s_mul_hi_i32 s4, s3, 0x66666667
	s_lshr_b32 s5, s4, 31
	s_ashr_i32 s4, s4, 1
	s_add_i32 s5, s4, s5
	s_lshl_b32 s4, s5, 3
	s_bfe_u32 s8, s2, 0x30002
	s_or_b32 s4, s4, s8
	s_mul_i32 s5, s5, 5
	s_sub_i32 s3, s3, s5
	s_lshl_b32 s24, s4, 7
	s_lshl_b32 s3, s3, 2
	s_and_b32 s2, s2, 3
	s_ashr_i32 s25, s24, 31
	s_or_b32 s26, s3, s2
	s_lshl_b64 s[2:3], s[24:25], 11
	s_add_u32 s2, s64, s2
	s_addc_u32 s3, s86, s3
	s_ashr_i32 s27, s26, 31
	v_mov_b32_e32 v4, v111
	s_lshl_b64 s[8:9], s[26:27], 18
	s_add_u32 s8, s93, s8
	v_ashrrev_i32_e32 v0, 3, v4
	v_lshrrev_b32_e32 v6, 4, v4
	v_xor_b32_e32 v8, v6, v4
	v_ashrrev_i32_e32 v1, 31, v0
	s_addc_u32 s9, s20, s9
	v_lshlrev_b64 v[0:1], 11, v[0:1]
	v_lshlrev_b32_e32 v8, 4, v8
	v_lshl_add_u64 v[2:3], s[2:3], 0, v[0:1]
	v_and_b32_e32 v108, 0x70, v8
	v_lshl_add_u64 v[0:1], s[8:9], 0, v[0:1]
	s_waitcnt vmcnt(11)
	v_lshlrev_b32_e32 v83, 4, v4
	v_lshl_add_u64 v[66:67], v[0:1], 0, v[108:109]
	v_readfirstlane_b32 s2, v83
	v_add_u32_e32 v0, 0x1000, v83
	v_lshl_add_u64 v[64:65], v[2:3], 0, v[108:109]
	s_mov_b32 m0, s2
	s_mov_b64 s[8:9], 0x10000
	v_readfirstlane_b32 s2, v0
	v_add_u32_e32 v0, 0x2000, v83
	s_cmp_eq_u32 s100, 1
	s_cbranch_scc1 .Lpf_a_skip0
	global_load_lds_dwordx4 v[64:65], off
.Lpf_a_skip0:
	v_lshl_add_u64 v[68:69], v[64:65], 0, s[8:9]
	s_mov_b32 m0, s2
	s_mov_b64 s[16:17], 0x20000
	v_readfirstlane_b32 s2, v0
	v_add_u32_e32 v0, 0x3000, v83
	s_cbranch_scc1 .Lpf_a_skip1
	global_load_lds_dwordx4 v[68:69], off
.Lpf_a_skip1:
	v_lshl_add_u64 v[70:71], v[64:65], 0, s[16:17]
	s_mov_b32 m0, s2
	s_mov_b64 s[28:29], 0x30000
	v_readfirstlane_b32 s2, v0
	v_add_u32_e32 v0, 0x4000, v83
	s_cbranch_scc1 .Lpf_a_skip2
	global_load_lds_dwordx4 v[70:71], off
.Lpf_a_skip2:
	v_lshl_add_u64 v[72:73], v[64:65], 0, s[28:29]
	s_mov_b32 m0, s2
	v_readfirstlane_b32 s2, v0
	v_add_u32_e32 v0, 0x5000, v83
	s_cbranch_scc1 .Lpf_a_skip3
	global_load_lds_dwordx4 v[72:73], off
.Lpf_a_skip3:
	s_mov_b32 m0, s2
	v_readfirstlane_b32 s2, v0
	v_add_u32_e32 v0, 0x6000, v83
	s_cbranch_scc1 .Lpf_a_skip4
	global_load_lds_dwordx4 v[66:67], off
.Lpf_a_skip4:
	v_lshl_add_u64 v[74:75], v[66:67], 0, s[8:9]
	s_mov_b32 m0, s2
	v_readfirstlane_b32 s2, v0
	v_add_u32_e32 v0, 0x7000, v83
	s_cbranch_scc1 .Lpf_a_skip5
	global_load_lds_dwordx4 v[74:75], off
.Lpf_a_skip5:
	v_lshl_add_u64 v[76:77], v[66:67], 0, s[16:17]
	s_mov_b32 m0, s2
	v_readfirstlane_b32 s2, v0
	s_cbranch_scc1 .Lpf_a_skip6
	global_load_lds_dwordx4 v[76:77], off
.Lpf_a_skip6:
	v_lshl_add_u64 v[78:79], v[66:67], 0, s[28:29]
	s_mov_b32 m0, s2
	v_and_b32_e32 v5, 15, v4
	s_cbranch_scc1 .Lpf_a_skip7
	global_load_lds_dwordx4 v[78:79], off
.Lpf_a_skip7:
	v_lshrrev_b32_e32 v0, 1, v4
	v_and_or_b32 v0, v0, s84, v5
	v_lshlrev_b32_e32 v81, 7, v0
	v_lshlrev_b32_e32 v0, 7, v4
	v_bfe_u32 v7, v4, 4, 2
	v_and_b32_e32 v80, 0x2780, v0
	v_bfe_u32 v0, v4, 1, 3
	v_bitop3_b32 v1, v6, v0, 3 bitop3:0x6c
	v_bitop3_b32 v0, v7, v0, 4 bitop3:0x36
	v_lshlrev_b32_e32 v82, 4, v0
	v_mov_b32_e32 v0, 0
	s_waitcnt vmcnt(0)
	v_lshlrev_b32_e32 v84, 4, v1
	s_mov_b32 s3, 0
	s_mov_b32 s2, 0x8000
	v_mov_b32_e32 v1, v0
	v_mov_b32_e32 v2, v0
	v_mov_b32_e32 v3, v0
	v_mov_b32_e32 v4, v0
	v_mov_b32_e32 v5, v0
	v_mov_b32_e32 v6, v0
	v_mov_b32_e32 v7, v0
	v_mov_b32_e32 v8, v0
	v_mov_b32_e32 v9, v0
	v_mov_b32_e32 v10, v0
	v_mov_b32_e32 v11, v0
	v_mov_b32_e32 v12, v0
	v_mov_b32_e32 v13, v0
	v_mov_b32_e32 v14, v0
	v_mov_b32_e32 v15, v0
	v_mov_b32_e32 v16, v0
	v_mov_b32_e32 v17, v0
	v_mov_b32_e32 v18, v0
	v_mov_b32_e32 v19, v0
	v_mov_b32_e32 v20, v0
	v_mov_b32_e32 v21, v0
	v_mov_b32_e32 v22, v0
	v_mov_b32_e32 v23, v0
	v_mov_b32_e32 v24, v0
	v_mov_b32_e32 v25, v0
	v_mov_b32_e32 v26, v0
	v_mov_b32_e32 v27, v0
	v_mov_b32_e32 v28, v0
	v_mov_b32_e32 v29, v0
	v_mov_b32_e32 v30, v0
	v_mov_b32_e32 v31, v0
	v_mov_b32_e32 v32, v0
	v_mov_b32_e32 v33, v0
	v_mov_b32_e32 v34, v0
	v_mov_b32_e32 v35, v0
	v_mov_b32_e32 v36, v0
	v_mov_b32_e32 v37, v0
	v_mov_b32_e32 v38, v0
	v_mov_b32_e32 v39, v0
	v_mov_b32_e32 v40, v0
	v_mov_b32_e32 v41, v0
	v_mov_b32_e32 v42, v0
	v_mov_b32_e32 v43, v0
	v_mov_b32_e32 v44, v0
	v_mov_b32_e32 v45, v0
	v_mov_b32_e32 v46, v0
	v_mov_b32_e32 v47, v0
	v_mov_b32_e32 v48, v0
	v_mov_b32_e32 v49, v0
	v_mov_b32_e32 v50, v0
	v_mov_b32_e32 v51, v0
	v_mov_b32_e32 v52, v0
	v_mov_b32_e32 v53, v0
	v_mov_b32_e32 v54, v0
	v_mov_b32_e32 v55, v0
	v_mov_b32_e32 v56, v0
	v_mov_b32_e32 v57, v0
	v_mov_b32_e32 v58, v0
	v_mov_b32_e32 v59, v0
	v_mov_b32_e32 v60, v0
	v_mov_b32_e32 v61, v0
	v_mov_b32_e32 v62, v0
	v_mov_b32_e32 v63, v0
	s_waitcnt vmcnt(0) lgkmcnt(0)
	s_barrier
	v_readfirstlane_b32 s16, v83
	s_mov_b64 s[98:99], 0x80
	v_lshl_add_u64 v[64:65], v[64:65], 0, s[98:99]
	v_lshl_add_u64 v[68:69], v[68:69], 0, s[98:99]
	v_lshl_add_u64 v[70:71], v[70:71], 0, s[98:99]
	v_lshl_add_u64 v[72:73], v[72:73], 0, s[98:99]
	v_lshl_add_u64 v[66:67], v[66:67], 0, s[98:99]
	v_lshl_add_u64 v[74:75], v[74:75], 0, s[98:99]
	v_lshl_add_u64 v[76:77], v[76:77], 0, s[98:99]
	v_lshl_add_u64 v[78:79], v[78:79], 0, s[98:99]
.LBB0_195:
	s_add_i32 s5, s2, 0xffff8000
	s_and_b32 s5, s5, 0x8000
	s_xor_b32 s3, s5, 0x8000
	s_add_u32 s3, s3, s16
	s_mov_b32 s8, s3
	s_mov_b32 m0, s8
	s_add_u32 s8, s3, 0x1000
	v_add_u32_e32 v85, s5, v81
	global_load_lds_dwordx4 v[64:65], off
	v_lshl_add_u64 v[64:65], v[64:65], 0, s[98:99]
	s_mov_b32 m0, s8
	s_add_u32 s8, s3, 0x2000
	v_or_b32_e32 v106, s5, v80
	global_load_lds_dwordx4 v[68:69], off
	v_lshl_add_u64 v[68:69], v[68:69], 0, s[98:99]
	s_mov_b32 m0, s8
	s_add_u32 s8, s3, 0x3000
	v_add_u32_e32 v250, v85, v84
	global_load_lds_dwordx4 v[70:71], off
	v_lshl_add_u64 v[70:71], v[70:71], 0, s[98:99]
	s_mov_b32 m0, s8
	s_add_u32 s8, s3, 0x4000
	v_add_u32_e32 v251, v106, v84
	global_load_lds_dwordx4 v[72:73], off
	v_lshl_add_u64 v[72:73], v[72:73], 0, s[98:99]
	s_mov_b32 m0, s8
	s_add_u32 s8, s3, 0x5000
	v_add_u32_e32 v252, v85, v82
	global_load_lds_dwordx4 v[66:67], off
	v_lshl_add_u64 v[66:67], v[66:67], 0, s[98:99]
	s_mov_b32 m0, s8
	s_add_u32 s8, s3, 0x6000
	v_add_u32_e32 v253, v106, v82
	global_load_lds_dwordx4 v[74:75], off
	v_lshl_add_u64 v[74:75], v[74:75], 0, s[98:99]
	s_mov_b32 m0, s8
	s_add_u32 s8, s3, 0x7000
	s_nop 0
	global_load_lds_dwordx4 v[76:77], off
	v_lshl_add_u64 v[76:77], v[76:77], 0, s[98:99]
	s_mov_b32 m0, s8
	s_add_u32 s8, s3, 0x8000
	s_nop 0
	global_load_lds_dwordx4 v[78:79], off
	v_lshl_add_u64 v[78:79], v[78:79], 0, s[98:99]
	ds_read_b128 v[86:89], v250
	ds_read_b128 v[102:105], v251 offset:16384
	ds_read_b128 v[122:125], v251 offset:18432
	ds_read_b128 v[126:129], v251 offset:20480
	ds_read_b128 v[130:133], v251 offset:22528
	ds_read_b128 v[90:93], v250 offset:2048
	ds_read_b128 v[94:97], v250 offset:4096
	ds_read_b128 v[98:101], v250 offset:6144
	ds_read_b128 v[218:221], v252
	ds_read_b128 v[234:237], v253 offset:16384
	ds_read_b128 v[238:241], v253 offset:18432
	ds_read_b128 v[242:245], v253 offset:20480
	ds_read_b128 v[246:249], v253 offset:22528
	ds_read_b128 v[222:225], v252 offset:2048
	ds_read_b128 v[226:229], v252 offset:4096
	s_waitcnt lgkmcnt(13)
	v_mfma_f32_16x16x32_bf16 v[60:63], v[86:89], v[102:105], v[60:63]
	ds_read_b128 v[230:233], v252 offset:6144
	s_waitcnt lgkmcnt(13)
	v_mfma_f32_16x16x32_bf16 v[56:59], v[86:89], v[122:125], v[56:59]
	s_waitcnt lgkmcnt(12)
	v_mfma_f32_16x16x32_bf16 v[52:55], v[86:89], v[126:129], v[52:55]
	s_waitcnt lgkmcnt(11)
	v_mfma_f32_16x16x32_bf16 v[48:51], v[86:89], v[130:133], v[48:51]
	s_waitcnt lgkmcnt(10)
	v_mfma_f32_16x16x32_bf16 v[44:47], v[90:93], v[102:105], v[44:47]
	v_mfma_f32_16x16x32_bf16 v[40:43], v[90:93], v[122:125], v[40:43]
	v_mfma_f32_16x16x32_bf16 v[36:39], v[90:93], v[126:129], v[36:39]
	v_mfma_f32_16x16x32_bf16 v[32:35], v[90:93], v[130:133], v[32:35]
	s_waitcnt lgkmcnt(9)
	v_mfma_f32_16x16x32_bf16 v[28:31], v[94:97], v[102:105], v[28:31]
	v_mfma_f32_16x16x32_bf16 v[24:27], v[94:97], v[122:125], v[24:27]
	v_mfma_f32_16x16x32_bf16 v[20:23], v[94:97], v[126:129], v[20:23]
	v_mfma_f32_16x16x32_bf16 v[16:19], v[94:97], v[130:133], v[16:19]
	s_waitcnt lgkmcnt(8)
	v_mfma_f32_16x16x32_bf16 v[12:15], v[98:101], v[102:105], v[12:15]
	v_mfma_f32_16x16x32_bf16 v[8:11], v[98:101], v[122:125], v[8:11]
	v_mfma_f32_16x16x32_bf16 v[4:7], v[98:101], v[126:129], v[4:7]
	v_mfma_f32_16x16x32_bf16 v[0:3], v[98:101], v[130:133], v[0:3]
	s_waitcnt lgkmcnt(6)
	v_mfma_f32_16x16x32_bf16 v[60:63], v[218:221], v[234:237], v[60:63]
	s_waitcnt lgkmcnt(5)
	v_mfma_f32_16x16x32_bf16 v[56:59], v[218:221], v[238:241], v[56:59]
	s_waitcnt lgkmcnt(4)
	v_mfma_f32_16x16x32_bf16 v[52:55], v[218:221], v[242:245], v[52:55]
	s_waitcnt lgkmcnt(3)
	v_mfma_f32_16x16x32_bf16 v[48:51], v[218:221], v[246:249], v[48:51]
	s_waitcnt lgkmcnt(2)
	v_mfma_f32_16x16x32_bf16 v[44:47], v[222:225], v[234:237], v[44:47]
	v_mfma_f32_16x16x32_bf16 v[40:43], v[222:225], v[238:241], v[40:43]
	v_mfma_f32_16x16x32_bf16 v[36:39], v[222:225], v[242:245], v[36:39]
	v_mfma_f32_16x16x32_bf16 v[32:35], v[222:225], v[246:249], v[32:35]
	s_waitcnt lgkmcnt(1)
	v_mfma_f32_16x16x32_bf16 v[28:31], v[226:229], v[234:237], v[28:31]
	v_mfma_f32_16x16x32_bf16 v[24:27], v[226:229], v[238:241], v[24:27]
	v_mfma_f32_16x16x32_bf16 v[20:23], v[226:229], v[242:245], v[20:23]
	v_mfma_f32_16x16x32_bf16 v[16:19], v[226:229], v[246:249], v[16:19]
	s_waitcnt lgkmcnt(0)
	v_mfma_f32_16x16x32_bf16 v[12:15], v[230:233], v[234:237], v[12:15]
	v_mfma_f32_16x16x32_bf16 v[8:11], v[230:233], v[238:241], v[8:11]
	v_mfma_f32_16x16x32_bf16 v[4:7], v[230:233], v[242:245], v[4:7]
	v_mfma_f32_16x16x32_bf16 v[0:3], v[230:233], v[246:249], v[0:3]
	s_add_i32 s2, s2, 0x8000
	s_cmp_lg_u32 s2, 0x80000
	s_waitcnt vmcnt(0)
	s_barrier
	s_cbranch_scc1 .LBB0_195
	s_mov_b32 s100, 0
	s_add_i32 s2, s92, s33
	s_add_i32 s2, s2, s85
	s_cmpk_gt_i32 s2, 0x167f
	s_cbranch_scc1 .Lpf_a_done
	s_ashr_i32 s3, s2, 5
	s_mul_hi_i32 s5, s3, 0x66666667
	s_lshr_b32 s8, s5, 31
	s_ashr_i32 s5, s5, 1
	s_add_i32 s5, s5, s8
	s_lshl_b32 s8, s5, 3
	s_bfe_u32 s9, s2, 0x30002
	s_or_b32 s8, s8, s9
	s_mul_i32 s5, s5, 5
	s_sub_i32 s3, s3, s5
	s_lshl_b32 s3, s3, 2
	s_and_b32 s9, s2, 3
	s_or_b32 s3, s3, s9
	s_lshr_b32 s9, s24, 7
	s_sub_i32 s8, s8, s9
	s_sub_i32 s2, s3, s26
	s_ashr_i32 s9, s8, 31
	s_lshl_b64 s[8:9], s[8:9], 18
	s_sub_u32 s8, s8, 0x800
	s_subb_u32 s9, s9, 0
	s_ashr_i32 s3, s2, 31
	s_lshl_b64 s[2:3], s[2:3], 18
	s_sub_u32 s2, s2, 0x800
	s_subb_u32 s3, s3, 0
	v_lshl_add_u64 v[250:251], v[64:65], 0, s[8:9]
	s_mov_b32 s5, s16
	s_mov_b32 m0, s5
	s_add_u32 s5, s16, 0x1000
	s_nop 0
	global_load_lds_dwordx4 v[250:251], off
	v_lshl_add_u64 v[250:251], v[68:69], 0, s[8:9]
	s_mov_b32 m0, s5
	s_add_u32 s5, s16, 0x2000
	s_nop 0
	global_load_lds_dwordx4 v[250:251], off
	v_lshl_add_u64 v[250:251], v[70:71], 0, s[8:9]
	s_mov_b32 m0, s5
	s_add_u32 s5, s16, 0x3000
	s_nop 0
	global_load_lds_dwordx4 v[250:251], off
	v_lshl_add_u64 v[250:251], v[72:73], 0, s[8:9]
	s_mov_b32 m0, s5
	s_add_u32 s5, s16, 0x4000
	s_nop 0
	global_load_lds_dwordx4 v[250:251], off
	v_lshl_add_u64 v[250:251], v[66:67], 0, s[2:3]
	s_mov_b32 m0, s5
	s_add_u32 s5, s16, 0x5000
	s_nop 0
	global_load_lds_dwordx4 v[250:251], off
	v_lshl_add_u64 v[250:251], v[74:75], 0, s[2:3]
	s_mov_b32 m0, s5
	s_add_u32 s5, s16, 0x6000
	s_nop 0
	global_load_lds_dwordx4 v[250:251], off
	v_lshl_add_u64 v[250:251], v[76:77], 0, s[2:3]
	s_mov_b32 m0, s5
	s_add_u32 s5, s16, 0x7000
	s_nop 0
	global_load_lds_dwordx4 v[250:251], off
	v_lshl_add_u64 v[250:251], v[78:79], 0, s[2:3]
	s_mov_b32 m0, s5
	s_add_u32 s5, s16, 0x8000
	s_nop 0
	global_load_lds_dwordx4 v[250:251], off
	v_mov_b32_e32 v250, 0
	s_mov_b32 s100, 1
.Lpf_a_done:
	v_add_u32_e32 v83, v81, v84
	ds_read_b128 v[64:67], v83 offset:32768
	v_add_u32_e32 v84, v80, v84
	ds_read_b128 v[68:71], v84 offset:49152
	ds_read_b128 v[72:75], v84 offset:51200
	ds_read_b128 v[76:79], v84 offset:53248
	ds_read_b128 v[84:87], v84 offset:55296
	v_add_u32_e32 v88, v81, v82
	v_add_u32_e32 v80, v80, v82
	s_waitcnt lgkmcnt(3)
	v_mfma_f32_16x16x32_bf16 v[60:63], v[64:67], v[68:71], v[60:63]
	s_waitcnt lgkmcnt(2)
	v_mfma_f32_16x16x32_bf16 v[56:59], v[64:67], v[72:75], v[56:59]
	s_waitcnt lgkmcnt(1)
	v_mfma_f32_16x16x32_bf16 v[52:55], v[64:67], v[76:79], v[52:55]
	s_waitcnt lgkmcnt(0)
	v_mfma_f32_16x16x32_bf16 v[48:51], v[64:67], v[84:87], v[48:51]
	ds_read_b128 v[64:67], v83 offset:34816
	s_waitcnt lgkmcnt(0)
	v_mfma_f32_16x16x32_bf16 v[44:47], v[64:67], v[68:71], v[44:47]
	v_mfma_f32_16x16x32_bf16 v[40:43], v[64:67], v[72:75], v[40:43]
	v_mfma_f32_16x16x32_bf16 v[36:39], v[64:67], v[76:79], v[36:39]
	v_mfma_f32_16x16x32_bf16 v[32:35], v[64:67], v[84:87], v[32:35]
	ds_read_b128 v[64:67], v83 offset:36864
	s_waitcnt lgkmcnt(0)
	v_mfma_f32_16x16x32_bf16 v[28:31], v[64:67], v[68:71], v[28:31]
	v_mfma_f32_16x16x32_bf16 v[24:27], v[64:67], v[72:75], v[24:27]
	v_mfma_f32_16x16x32_bf16 v[20:23], v[64:67], v[76:79], v[20:23]
	v_mfma_f32_16x16x32_bf16 v[16:19], v[64:67], v[84:87], v[16:19]
	ds_read_b128 v[64:67], v83 offset:38912
	s_waitcnt lgkmcnt(0)
	v_mfma_f32_16x16x32_bf16 v[12:15], v[64:67], v[68:71], v[12:15]
	ds_read_b128 v[68:71], v88 offset:32768
	v_mfma_f32_16x16x32_bf16 v[8:11], v[64:67], v[72:75], v[8:11]
	ds_read_b128 v[72:75], v80 offset:51200
	v_mfma_f32_16x16x32_bf16 v[4:7], v[64:67], v[76:79], v[4:7]
	ds_read_b128 v[76:79], v80 offset:53248
	v_mfma_f32_16x16x32_bf16 v[0:3], v[64:67], v[84:87], v[0:3]
	ds_read_b128 v[64:67], v80 offset:49152
	ds_read_b128 v[80:83], v80 offset:55296
	s_waitcnt lgkmcnt(1)
	v_mfma_f32_16x16x32_bf16 v[60:63], v[68:71], v[64:67], v[60:63]
	v_mfma_f32_16x16x32_bf16 v[56:59], v[68:71], v[72:75], v[56:59]
	v_mfma_f32_16x16x32_bf16 v[52:55], v[68:71], v[76:79], v[52:55]
	s_waitcnt lgkmcnt(0)
	v_mfma_f32_16x16x32_bf16 v[48:51], v[68:71], v[80:83], v[48:51]
	ds_read_b128 v[68:71], v88 offset:34816
	s_waitcnt lgkmcnt(0)
	v_mfma_f32_16x16x32_bf16 v[44:47], v[68:71], v[64:67], v[44:47]
	v_mfma_f32_16x16x32_bf16 v[40:43], v[68:71], v[72:75], v[40:43]
	v_mfma_f32_16x16x32_bf16 v[36:39], v[68:71], v[76:79], v[36:39]
	v_mfma_f32_16x16x32_bf16 v[32:35], v[68:71], v[80:83], v[32:35]
	ds_read_b128 v[68:71], v88 offset:36864
	s_waitcnt lgkmcnt(0)
	v_mfma_f32_16x16x32_bf16 v[28:31], v[68:71], v[64:67], v[28:31]
	v_mfma_f32_16x16x32_bf16 v[24:27], v[68:71], v[72:75], v[24:27]
	v_mfma_f32_16x16x32_bf16 v[20:23], v[68:71], v[76:79], v[20:23]
	v_mfma_f32_16x16x32_bf16 v[16:19], v[68:71], v[80:83], v[16:19]
	ds_read_b128 v[68:71], v88 offset:38912
	s_waitcnt lgkmcnt(0)
	v_mfma_f32_16x16x32_bf16 v[12:15], v[68:71], v[64:67], v[12:15]
	v_mfma_f32_16x16x32_bf16 v[8:11], v[68:71], v[72:75], v[8:11]
	v_mfma_f32_16x16x32_bf16 v[4:7], v[68:71], v[76:79], v[4:7]
	v_mfma_f32_16x16x32_bf16 v[0:3], v[68:71], v[80:83], v[0:3]
	v_mov_b32_e32 v88, v111
	s_barrier
	s_cmp_gt_i32 s26, 12
	v_ashrrev_i32_e32 v86, 7, v88
	v_bfe_u32 v85, v88, 6, 1
	v_and_b32_e32 v84, 15, v88
	v_bfe_u32 v87, v88, 4, 2
	s_mov_b64 s[2:3], -1
	s_cbranch_scc0 .LBB0_398
	s_add_i32 s2, s24, 0xfffff000
	s_ashr_i32 s8, s4, 1
	s_cmp_lt_i32 s4, 32
	s_cselect_b64 s[28:29], -1, 0
	s_lshr_b32 s9, s2, 12
	s_cmp_gt_i32 s4, 31
	s_cselect_b64 s[2:3], -1, 0
	s_and_b64 s[4:5], s[2:3], exec
	s_movk_i32 s4, 0xf80
	s_cselect_b32 s4, s4, 0x80
	s_cselect_b32 s30, s9, s8
	s_and_b32 s25, s4, s24
	s_cmp_lg_u32 s26, 13
	s_mov_b64 s[4:5], -1
	s_cbranch_scc0 .LBB0_330
	s_cmp_gt_u32 s26, 18
	s_cbranch_scc0 .LBB0_232
	s_and_b64 s[4:5], s[2:3], exec
	s_mov_b32 s4, 0x105dc000
	s_cselect_b32 s4, s4, 0x10ddc000
	s_add_u32 s16, s60, s4
	s_addc_u32 s17, s62, 0
	s_ashr_i32 s31, s30, 31
	s_lshl_b64 s[4:5], s[30:31], 7
	v_lshl_add_u32 v64, v86, 6, s25
	s_and_b64 s[2:3], s[2:3], exec
	v_lshl_or_b32 v64, v87, 2, v64
	v_lshlrev_b32_e32 v76, 6, v85
	s_cselect_b32 s8, 12, 8
	s_lshl_b64 s[2:3], s[30:31], 10
	v_or_b32_e32 v89, s4, v76
	s_add_u32 s4, s2, s6
	v_ashrrev_i32_e32 v65, 31, v64
	v_mov_b32_e32 v73, s5
	s_addc_u32 s5, s3, s7
	v_lshl_add_u64 v[80:81], v[64:65], 1, s[16:17]
	v_lshl_add_u64 v[68:69], s[4:5], 0, v[64:65]
	v_or_b32_e32 v72, v89, v84
	v_lshlrev_b64 v[66:67], s8, v[72:73]
	v_cndmask_b32_e64 v65, 0, 1, s[28:29]
	v_lshlrev_b64 v[74:75], 9, v[68:69]
	v_cvt_pk_bf16_f32 v70, v60, v61
	v_cvt_pk_bf16_f32 v71, v62, v63
	v_lshl_add_u64 v[66:67], v[66:67], 1, v[80:81]
	v_cmp_ne_u32_e64 s[2:3], 1, v65
	s_andn2_b64 vcc, exec, s[28:29]
	v_lshl_add_u64 v[82:83], s[0:1], 0, v[74:75]
	v_lshlrev_b32_e32 v108, 2, v76
	v_or_b32_e32 v78, 0x200, v74
	v_or_b32_e32 v76, 0x400, v74
	v_or_b32_e32 v74, 0x600, v74
	global_store_dwordx2 v[66:67], v[70:71], off
	s_cbranch_vccnz .LBB0_201
	v_lshl_add_u64 v[68:69], v[82:83], 0, v[108:109]
	v_lshlrev_b32_e32 v70, 2, v84
	v_mov_b32_e32 v71, v109
	v_lshl_add_u64 v[68:69], v[68:69], 0, v[70:71]
	v_add_co_u32_e32 v68, vcc, 0xaa00000, v68
	v_mov_b32_e32 v79, v75
	s_nop 0
	v_addc_co_u32_e32 v69, vcc, 0, v69, vcc
	global_store_dword v[68:69], v60, off
	v_lshl_add_u64 v[68:69], s[0:1], 0, v[78:79]
	v_lshl_add_u64 v[68:69], v[68:69], 0, v[108:109]
	v_lshl_add_u64 v[68:69], v[68:69], 0, v[70:71]
	v_add_co_u32_e32 v68, vcc, 0xaa00000, v68
	v_mov_b32_e32 v77, v75
	s_nop 0
	v_addc_co_u32_e32 v69, vcc, 0, v69, vcc
	global_store_dword v[68:69], v61, off
	v_lshl_add_u64 v[68:69], s[0:1], 0, v[76:77]
	v_lshl_add_u64 v[68:69], v[68:69], 0, v[108:109]
	v_lshl_add_u64 v[68:69], v[68:69], 0, v[70:71]
	v_add_co_u32_e32 v68, vcc, 0xaa00000, v68
	s_nop 1
	v_addc_co_u32_e32 v69, vcc, 0, v69, vcc
	global_store_dword v[68:69], v62, off
	v_lshl_add_u64 v[68:69], s[0:1], 0, v[74:75]
	v_lshl_add_u64 v[68:69], v[68:69], 0, v[108:109]
	v_lshl_add_u64 v[68:69], v[68:69], 0, v[70:71]
	v_add_co_u32_e32 v68, vcc, 0xaa00000, v68
	s_nop 1
	v_addc_co_u32_e32 v69, vcc, 0, v69, vcc
	global_store_dword v[68:69], v63, off

.LBB0_1036:
	s_or_b64 exec, exec, s[2:3]
	s_mov_b64 s[0:1], 0
	v_readlane_b32 s16, v215, 6
	s_barrier
	v_readlane_b32 s30, v215, 20
	v_readlane_b32 s31, v215, 21
	s_add_u32 s0, s30, s0
	s_addc_u32 s9, s31, s1
	v_readlane_b32 s24, v215, 14
	s_add_u32 s1, s0, 0x17fc000
	s_addc_u32 s24, s9, 0
	v_readlane_b32 s2, v215, 31
	s_add_u32 s2, s0, s2
	v_readlane_b32 s25, v215, 15
	s_addc_u32 s3, s9, 0
	v_readlane_b32 s26, v215, 16
	s_add_u32 s25, s2, 0x500000
	v_readlane_b32 s27, v215, 17
	s_addc_u32 s26, s3, 0
	v_readlane_b32 s28, v215, 18
	s_add_u32 s27, s0, 0xfc5c000
	s_addc_u32 s28, s9, 0
	s_add_u32 s2, s0, 0x5ffc000
	s_addc_u32 s3, s9, 0
	s_add_u32 s4, s0, 0xd85c000
	s_addc_u32 s5, s9, 0
	s_add_u32 s6, s0, 0xa7fc000
	s_addc_u32 s7, s9, 0
	v_readlane_b32 s29, v215, 19
	s_add_u32 s8, s0, 0x1915c000
	s_addc_u32 s9, s9, 0
	s_mov_b32 s29, 0
	s_mov_b32 s100, 0
	v_readlane_b32 s17, v215, 7
	v_readlane_b32 s18, v215, 8
	v_readlane_b32 s19, v215, 9
	v_readlane_b32 s20, v215, 10
	v_readlane_b32 s21, v215, 11
	v_readlane_b32 s22, v215, 12
	v_readlane_b32 s23, v215, 13
	s_branch .LBB0_1039

.LBB0_1039:
	s_add_i32 s10, s29, s85
	s_cmpk_gt_i32 s10, 0x2cff
	s_cbranch_scc1 .LBB0_1038
	s_ashr_i32 s0, s10, 6
	s_mul_hi_i32 s11, s0, 0x66666667
	s_lshr_b32 s16, s11, 31
	s_ashr_i32 s11, s11, 1
	s_add_i32 s11, s11, s16
	s_mul_i32 s16, s11, 5
	s_sub_i32 s0, s0, s16
	s_lshl_b32 s20, s0, 3
	s_and_b32 s0, s10, 7
	s_lshl_b32 s10, s10, 4
	s_lshl_b32 s11, s11, 10
	s_and_b32 s10, s10, 0x380
	s_or_b32 s10, s11, s10
	s_ashr_i32 s11, s10, 31
	s_or_b32 s16, s20, s0
	s_lshl_b64 s[18:19], s[10:11], 11
	s_add_u32 s18, s1, s18
	s_addc_u32 s19, s24, s19
	s_ashr_i32 s17, s16, 31
	v_mov_b32_e32 v4, v111
	s_lshl_b64 s[22:23], s[16:17], 18
	s_add_u32 s22, s25, s22
	v_ashrrev_i32_e32 v0, 3, v4
	v_lshrrev_b32_e32 v6, 4, v4
	v_xor_b32_e32 v8, v6, v4
	v_ashrrev_i32_e32 v1, 31, v0
	s_addc_u32 s23, s26, s23
	v_lshlrev_b64 v[0:1], 11, v[0:1]
	v_lshlrev_b32_e32 v8, 4, v8
	v_lshl_add_u64 v[2:3], s[18:19], 0, v[0:1]
	v_and_b32_e32 v108, 0x70, v8
	v_lshl_add_u64 v[0:1], s[22:23], 0, v[0:1]
	s_waitcnt vmcnt(11)
	v_lshlrev_b32_e32 v83, 4, v4
	v_lshl_add_u64 v[66:67], v[0:1], 0, v[108:109]
	v_readfirstlane_b32 s11, v83
	v_add_u32_e32 v0, 0x1000, v83
	v_lshl_add_u64 v[64:65], v[2:3], 0, v[108:109]
	s_mov_b32 m0, s11
	s_mov_b64 s[18:19], 0x10000
	v_readfirstlane_b32 s11, v0
	v_add_u32_e32 v0, 0x2000, v83
	s_cmp_eq_u32 s100, 1
	s_cbranch_scc1 .Lpf_g_skip0
	global_load_lds_dwordx4 v[64:65], off
.Lpf_g_skip0:
	v_lshl_add_u64 v[68:69], v[64:65], 0, s[18:19]
	s_mov_b32 m0, s11
	s_mov_b64 s[22:23], 0x20000
	v_readfirstlane_b32 s11, v0
	v_add_u32_e32 v0, 0x3000, v83
	s_cbranch_scc1 .Lpf_g_skip1
	global_load_lds_dwordx4 v[68:69], off
.Lpf_g_skip1:
	v_lshl_add_u64 v[70:71], v[64:65], 0, s[22:23]
	s_mov_b32 m0, s11
	s_mov_b64 s[30:31], 0x30000
	v_readfirstlane_b32 s11, v0
	v_add_u32_e32 v0, 0x4000, v83
	s_cbranch_scc1 .Lpf_g_skip2
	global_load_lds_dwordx4 v[70:71], off
.Lpf_g_skip2:
	v_lshl_add_u64 v[72:73], v[64:65], 0, s[30:31]
	s_mov_b32 m0, s11
	v_readfirstlane_b32 s11, v0
	v_add_u32_e32 v0, 0x5000, v83
	s_cbranch_scc1 .Lpf_g_skip3
	global_load_lds_dwordx4 v[72:73], off
.Lpf_g_skip3:
	s_mov_b32 m0, s11
	v_readfirstlane_b32 s11, v0
	v_add_u32_e32 v0, 0x6000, v83
	s_cbranch_scc1 .Lpf_g_skip4
	global_load_lds_dwordx4 v[66:67], off
.Lpf_g_skip4:
	v_lshl_add_u64 v[74:75], v[66:67], 0, s[18:19]
	s_mov_b32 m0, s11
	v_readfirstlane_b32 s11, v0
	v_add_u32_e32 v0, 0x7000, v83
	s_cbranch_scc1 .Lpf_g_skip5
	global_load_lds_dwordx4 v[74:75], off
.Lpf_g_skip5:
	v_lshl_add_u64 v[76:77], v[66:67], 0, s[22:23]
	s_mov_b32 m0, s11
	v_readfirstlane_b32 s11, v0
	s_cbranch_scc1 .Lpf_g_skip6
	global_load_lds_dwordx4 v[76:77], off
.Lpf_g_skip6:
	v_lshl_add_u64 v[78:79], v[66:67], 0, s[30:31]
	s_mov_b32 m0, s11
	v_and_b32_e32 v5, 15, v4
	s_cbranch_scc1 .Lpf_g_skip7
	global_load_lds_dwordx4 v[78:79], off
.Lpf_g_skip7:
	v_lshrrev_b32_e32 v0, 1, v4
	v_and_or_b32 v0, v0, s84, v5
	v_lshlrev_b32_e32 v80, 7, v0
	v_lshlrev_b32_e32 v0, 7, v4
	v_bfe_u32 v7, v4, 4, 2
	v_and_b32_e32 v81, 0x2780, v0
	v_bfe_u32 v0, v4, 1, 3
	v_bitop3_b32 v1, v6, v0, 3 bitop3:0x6c
	v_bitop3_b32 v0, v7, v0, 4 bitop3:0x36
	v_lshlrev_b32_e32 v82, 4, v0
	v_mov_b32_e32 v0, 0
	s_waitcnt vmcnt(0)
	v_lshlrev_b32_e32 v84, 4, v1
	s_mov_b32 s17, 0
	s_mov_b32 s11, 0x8000
	v_mov_b32_e32 v1, v0
	v_mov_b32_e32 v2, v0
	v_mov_b32_e32 v3, v0
	v_mov_b32_e32 v4, v0
	v_mov_b32_e32 v5, v0
	v_mov_b32_e32 v6, v0
	v_mov_b32_e32 v7, v0
	v_mov_b32_e32 v8, v0
	v_mov_b32_e32 v9, v0
	v_mov_b32_e32 v10, v0
	v_mov_b32_e32 v11, v0
	v_mov_b32_e32 v12, v0
	v_mov_b32_e32 v13, v0
	v_mov_b32_e32 v14, v0
	v_mov_b32_e32 v15, v0
	v_mov_b32_e32 v16, v0
	v_mov_b32_e32 v17, v0
	v_mov_b32_e32 v18, v0
	v_mov_b32_e32 v19, v0
	v_mov_b32_e32 v20, v0
	v_mov_b32_e32 v21, v0
	v_mov_b32_e32 v22, v0
	v_mov_b32_e32 v23, v0
	v_mov_b32_e32 v24, v0
	v_mov_b32_e32 v25, v0
	v_mov_b32_e32 v26, v0
	v_mov_b32_e32 v27, v0
	v_mov_b32_e32 v28, v0
	v_mov_b32_e32 v29, v0
	v_mov_b32_e32 v30, v0
	v_mov_b32_e32 v31, v0
	v_mov_b32_e32 v32, v0
	v_mov_b32_e32 v33, v0
	v_mov_b32_e32 v34, v0
	v_mov_b32_e32 v35, v0
	v_mov_b32_e32 v36, v0
	v_mov_b32_e32 v37, v0
	v_mov_b32_e32 v38, v0
	v_mov_b32_e32 v39, v0
	v_mov_b32_e32 v40, v0
	v_mov_b32_e32 v41, v0
	v_mov_b32_e32 v42, v0
	v_mov_b32_e32 v43, v0
	v_mov_b32_e32 v44, v0
	v_mov_b32_e32 v45, v0
	v_mov_b32_e32 v46, v0
	v_mov_b32_e32 v47, v0
	v_mov_b32_e32 v48, v0
	v_mov_b32_e32 v49, v0
	v_mov_b32_e32 v50, v0
	v_mov_b32_e32 v51, v0
	v_mov_b32_e32 v52, v0
	v_mov_b32_e32 v53, v0
	v_mov_b32_e32 v54, v0
	v_mov_b32_e32 v55, v0
	v_mov_b32_e32 v56, v0
	v_mov_b32_e32 v57, v0
	v_mov_b32_e32 v58, v0
	v_mov_b32_e32 v59, v0
	v_mov_b32_e32 v60, v0
	v_mov_b32_e32 v61, v0
	v_mov_b32_e32 v62, v0
	v_mov_b32_e32 v63, v0
	s_waitcnt lgkmcnt(0)
	s_barrier
	v_readfirstlane_b32 s22, v83
	s_mov_b64 s[98:99], 0x80
	v_lshl_add_u64 v[64:65], v[64:65], 0, s[98:99]
	v_lshl_add_u64 v[68:69], v[68:69], 0, s[98:99]
	v_lshl_add_u64 v[70:71], v[70:71], 0, s[98:99]
	v_lshl_add_u64 v[72:73], v[72:73], 0, s[98:99]
	v_lshl_add_u64 v[66:67], v[66:67], 0, s[98:99]
	v_lshl_add_u64 v[74:75], v[74:75], 0, s[98:99]
	v_lshl_add_u64 v[76:77], v[76:77], 0, s[98:99]
	v_lshl_add_u64 v[78:79], v[78:79], 0, s[98:99]
.LBB0_1041:
	s_add_i32 s21, s11, 0xffff8000
	s_and_b32 s21, s21, 0x8000
	s_xor_b32 s17, s21, 0x8000
	s_add_u32 s17, s17, s22
	s_mov_b32 s18, s17
	s_mov_b32 m0, s18
	s_add_u32 s18, s17, 0x1000
	v_add_u32_e32 v85, s21, v80
	global_load_lds_dwordx4 v[64:65], off
	v_lshl_add_u64 v[64:65], v[64:65], 0, s[98:99]
	s_mov_b32 m0, s18
	s_add_u32 s18, s17, 0x2000
	v_or_b32_e32 v106, s21, v81
	global_load_lds_dwordx4 v[68:69], off
	v_lshl_add_u64 v[68:69], v[68:69], 0, s[98:99]
	s_mov_b32 m0, s18
	s_add_u32 s18, s17, 0x3000
	v_add_u32_e32 v250, v85, v84
	global_load_lds_dwordx4 v[70:71], off
	v_lshl_add_u64 v[70:71], v[70:71], 0, s[98:99]
	s_mov_b32 m0, s18
	s_add_u32 s18, s17, 0x4000
	v_add_u32_e32 v251, v106, v84
	global_load_lds_dwordx4 v[72:73], off
	v_lshl_add_u64 v[72:73], v[72:73], 0, s[98:99]
	s_mov_b32 m0, s18
	s_add_u32 s18, s17, 0x5000
	v_add_u32_e32 v252, v85, v82
	global_load_lds_dwordx4 v[66:67], off
	v_lshl_add_u64 v[66:67], v[66:67], 0, s[98:99]
	s_mov_b32 m0, s18
	s_add_u32 s18, s17, 0x6000
	v_add_u32_e32 v253, v106, v82
	global_load_lds_dwordx4 v[74:75], off
	v_lshl_add_u64 v[74:75], v[74:75], 0, s[98:99]
	s_mov_b32 m0, s18
	s_add_u32 s18, s17, 0x7000
	s_nop 0
	global_load_lds_dwordx4 v[76:77], off
	v_lshl_add_u64 v[76:77], v[76:77], 0, s[98:99]
	s_mov_b32 m0, s18
	s_add_u32 s18, s17, 0x8000
	s_nop 0
	global_load_lds_dwordx4 v[78:79], off
	v_lshl_add_u64 v[78:79], v[78:79], 0, s[98:99]
	ds_read_b128 v[86:89], v250
	ds_read_b128 v[102:105], v251 offset:16384
	ds_read_b128 v[122:125], v251 offset:18432
	ds_read_b128 v[126:129], v251 offset:20480
	ds_read_b128 v[130:133], v251 offset:22528
	ds_read_b128 v[90:93], v250 offset:2048
	ds_read_b128 v[94:97], v250 offset:4096
	ds_read_b128 v[98:101], v250 offset:6144
	ds_read_b128 v[218:221], v252
	ds_read_b128 v[234:237], v253 offset:16384
	ds_read_b128 v[238:241], v253 offset:18432
	ds_read_b128 v[242:245], v253 offset:20480
	ds_read_b128 v[246:249], v253 offset:22528
	ds_read_b128 v[222:225], v252 offset:2048
	ds_read_b128 v[226:229], v252 offset:4096
	s_waitcnt lgkmcnt(13)
	v_mfma_f32_16x16x32_bf16 v[60:63], v[102:105], v[86:89], v[60:63]
	ds_read_b128 v[230:233], v252 offset:6144
	s_waitcnt lgkmcnt(13)
	v_mfma_f32_16x16x32_bf16 v[56:59], v[122:125], v[86:89], v[56:59]
	s_waitcnt lgkmcnt(12)
	v_mfma_f32_16x16x32_bf16 v[52:55], v[126:129], v[86:89], v[52:55]
	s_waitcnt lgkmcnt(11)
	v_mfma_f32_16x16x32_bf16 v[48:51], v[130:133], v[86:89], v[48:51]
	s_waitcnt lgkmcnt(10)
	v_mfma_f32_16x16x32_bf16 v[44:47], v[102:105], v[90:93], v[44:47]
	v_mfma_f32_16x16x32_bf16 v[40:43], v[122:125], v[90:93], v[40:43]
	v_mfma_f32_16x16x32_bf16 v[36:39], v[126:129], v[90:93], v[36:39]
	v_mfma_f32_16x16x32_bf16 v[32:35], v[130:133], v[90:93], v[32:35]
	s_waitcnt lgkmcnt(9)
	v_mfma_f32_16x16x32_bf16 v[28:31], v[102:105], v[94:97], v[28:31]
	v_mfma_f32_16x16x32_bf16 v[24:27], v[122:125], v[94:97], v[24:27]
	v_mfma_f32_16x16x32_bf16 v[20:23], v[126:129], v[94:97], v[20:23]
	v_mfma_f32_16x16x32_bf16 v[16:19], v[130:133], v[94:97], v[16:19]
	s_waitcnt lgkmcnt(8)
	v_mfma_f32_16x16x32_bf16 v[12:15], v[102:105], v[98:101], v[12:15]
	v_mfma_f32_16x16x32_bf16 v[8:11], v[122:125], v[98:101], v[8:11]
	v_mfma_f32_16x16x32_bf16 v[4:7], v[126:129], v[98:101], v[4:7]
	v_mfma_f32_16x16x32_bf16 v[0:3], v[130:133], v[98:101], v[0:3]
	s_waitcnt lgkmcnt(6)
	v_mfma_f32_16x16x32_bf16 v[60:63], v[234:237], v[218:221], v[60:63]
	s_waitcnt lgkmcnt(5)
	v_mfma_f32_16x16x32_bf16 v[56:59], v[238:241], v[218:221], v[56:59]
	s_waitcnt lgkmcnt(4)
	v_mfma_f32_16x16x32_bf16 v[52:55], v[242:245], v[218:221], v[52:55]
	s_waitcnt lgkmcnt(3)
	v_mfma_f32_16x16x32_bf16 v[48:51], v[246:249], v[218:221], v[48:51]
	s_waitcnt lgkmcnt(2)
	v_mfma_f32_16x16x32_bf16 v[44:47], v[234:237], v[222:225], v[44:47]
	v_mfma_f32_16x16x32_bf16 v[40:43], v[238:241], v[222:225], v[40:43]
	v_mfma_f32_16x16x32_bf16 v[36:39], v[242:245], v[222:225], v[36:39]
	v_mfma_f32_16x16x32_bf16 v[32:35], v[246:249], v[222:225], v[32:35]
	s_waitcnt lgkmcnt(1)
	v_mfma_f32_16x16x32_bf16 v[28:31], v[234:237], v[226:229], v[28:31]
	v_mfma_f32_16x16x32_bf16 v[24:27], v[238:241], v[226:229], v[24:27]
	v_mfma_f32_16x16x32_bf16 v[20:23], v[242:245], v[226:229], v[20:23]
	v_mfma_f32_16x16x32_bf16 v[16:19], v[246:249], v[226:229], v[16:19]
	s_waitcnt lgkmcnt(0)
	v_mfma_f32_16x16x32_bf16 v[12:15], v[234:237], v[230:233], v[12:15]
	v_mfma_f32_16x16x32_bf16 v[8:11], v[238:241], v[230:233], v[8:11]
	v_mfma_f32_16x16x32_bf16 v[4:7], v[242:245], v[230:233], v[4:7]
	v_mfma_f32_16x16x32_bf16 v[0:3], v[246:249], v[230:233], v[0:3]
	s_add_i32 s11, s11, 0x8000
	s_cmp_lg_u32 s11, 0x80000
	s_waitcnt vmcnt(0)
	s_barrier
	s_cbranch_scc1 .LBB0_1041
	s_mov_b32 s100, 0
	s_add_i32 s11, s29, s33
	s_add_i32 s11, s11, s85
	s_cmpk_gt_i32 s11, 0x2cff
	s_cbranch_scc1 .Lpf_g_done
	s_ashr_i32 s17, s11, 6
	s_mul_hi_i32 s18, s17, 0x66666667
	s_lshr_b32 s19, s18, 31
	s_ashr_i32 s18, s18, 1
	s_add_i32 s18, s18, s19
	s_mul_i32 s19, s18, 5
	s_sub_i32 s17, s17, s19
	s_lshl_b32 s17, s17, 3
	s_and_b32 s19, s11, 7
	s_or_b32 s17, s17, s19
	s_lshl_b32 s18, s18, 10
	s_lshl_b32 s19, s11, 4
	s_and_b32 s19, s19, 0x380
	s_or_b32 s18, s18, s19
	s_sub_i32 s18, s18, s10
	s_or_b32 s19, s20, s0
	s_sub_i32 s17, s17, s19
	s_ashr_i32 s19, s18, 31
	s_lshl_b64 s[18:19], s[18:19], 11
	s_sub_u32 s18, s18, 0x800
	s_subb_u32 s19, s19, 0
	s_mov_b32 s98, s17
	s_ashr_i32 s99, s98, 31
	s_lshl_b64 s[98:99], s[98:99], 18
	s_sub_u32 s98, s98, 0x800
	s_subb_u32 s99, s99, 0
	v_lshl_add_u64 v[250:251], v[64:65], 0, s[18:19]
	s_mov_b32 s11, s22
	s_mov_b32 m0, s11
	s_add_u32 s11, s22, 0x1000
	s_nop 0
	global_load_lds_dwordx4 v[250:251], off
	v_lshl_add_u64 v[250:251], v[68:69], 0, s[18:19]
	s_mov_b32 m0, s11
	s_add_u32 s11, s22, 0x2000
	s_nop 0
	global_load_lds_dwordx4 v[250:251], off
	v_lshl_add_u64 v[250:251], v[70:71], 0, s[18:19]
	s_mov_b32 m0, s11
	s_add_u32 s11, s22, 0x3000
	s_nop 0
	global_load_lds_dwordx4 v[250:251], off
	v_lshl_add_u64 v[250:251], v[72:73], 0, s[18:19]
	s_mov_b32 m0, s11
	s_add_u32 s11, s22, 0x4000
	s_nop 0
	global_load_lds_dwordx4 v[250:251], off
	v_lshl_add_u64 v[250:251], v[66:67], 0, s[98:99]
	s_mov_b32 m0, s11
	s_add_u32 s11, s22, 0x5000
	s_nop 0
	global_load_lds_dwordx4 v[250:251], off
	v_lshl_add_u64 v[250:251], v[74:75], 0, s[98:99]
	s_mov_b32 m0, s11
	s_add_u32 s11, s22, 0x6000
	s_nop 0
	global_load_lds_dwordx4 v[250:251], off
	v_lshl_add_u64 v[250:251], v[76:77], 0, s[98:99]
	s_mov_b32 m0, s11
	s_add_u32 s11, s22, 0x7000
	s_nop 0
	global_load_lds_dwordx4 v[250:251], off
	v_lshl_add_u64 v[250:251], v[78:79], 0, s[98:99]
	s_mov_b32 m0, s11
	s_add_u32 s11, s22, 0x8000
	s_nop 0
	global_load_lds_dwordx4 v[250:251], off
	v_mov_b32_e32 v250, 0
	s_mov_b32 s100, 1
.Lpf_g_done:
	v_add_u32_e32 v83, v81, v84
	ds_read_b128 v[64:67], v83 offset:49152
	ds_read_b128 v[72:75], v83 offset:51200
	v_add_u32_e32 v88, v80, v84
	ds_read_b128 v[76:79], v83 offset:53248
	ds_read_b128 v[84:87], v83 offset:55296
	ds_read_b128 v[68:71], v88 offset:32768
	v_add_u32_e32 v81, v81, v82
	s_waitcnt lgkmcnt(0)
	v_mfma_f32_16x16x32_bf16 v[60:63], v[64:67], v[68:71], v[60:63]
	v_mfma_f32_16x16x32_bf16 v[56:59], v[72:75], v[68:71], v[56:59]
	v_mfma_f32_16x16x32_bf16 v[52:55], v[76:79], v[68:71], v[52:55]
	v_mfma_f32_16x16x32_bf16 v[48:51], v[84:87], v[68:71], v[48:51]
	ds_read_b128 v[68:71], v88 offset:34816
	s_waitcnt lgkmcnt(0)
	v_mfma_f32_16x16x32_bf16 v[44:47], v[64:67], v[68:71], v[44:47]
	v_mfma_f32_16x16x32_bf16 v[40:43], v[72:75], v[68:71], v[40:43]
	v_mfma_f32_16x16x32_bf16 v[36:39], v[76:79], v[68:71], v[36:39]
	v_mfma_f32_16x16x32_bf16 v[32:35], v[84:87], v[68:71], v[32:35]
	ds_read_b128 v[68:71], v88 offset:36864
	s_waitcnt lgkmcnt(0)
	v_mfma_f32_16x16x32_bf16 v[28:31], v[64:67], v[68:71], v[28:31]
	v_mfma_f32_16x16x32_bf16 v[24:27], v[72:75], v[68:71], v[24:27]
	v_mfma_f32_16x16x32_bf16 v[20:23], v[76:79], v[68:71], v[20:23]
	v_mfma_f32_16x16x32_bf16 v[16:19], v[84:87], v[68:71], v[16:19]
	ds_read_b128 v[68:71], v88 offset:38912
	s_waitcnt lgkmcnt(0)
	v_mfma_f32_16x16x32_bf16 v[0:3], v[84:87], v[68:71], v[0:3]
	v_add_u32_e32 v84, v80, v82
	v_mfma_f32_16x16x32_bf16 v[12:15], v[64:67], v[68:71], v[12:15]
	ds_read_b128 v[64:67], v81 offset:49152
	v_mfma_f32_16x16x32_bf16 v[8:11], v[72:75], v[68:71], v[8:11]
	ds_read_b128 v[72:75], v81 offset:51200
	v_mfma_f32_16x16x32_bf16 v[4:7], v[76:79], v[68:71], v[4:7]
	ds_read_b128 v[68:71], v84 offset:32768
	ds_read_b128 v[76:79], v81 offset:53248
	ds_read_b128 v[80:83], v81 offset:55296
	s_waitcnt lgkmcnt(2)
	v_mfma_f32_16x16x32_bf16 v[60:63], v[64:67], v[68:71], v[60:63]
	v_mfma_f32_16x16x32_bf16 v[56:59], v[72:75], v[68:71], v[56:59]
	s_waitcnt lgkmcnt(1)
	v_mfma_f32_16x16x32_bf16 v[52:55], v[76:79], v[68:71], v[52:55]
	s_waitcnt lgkmcnt(0)
	v_mfma_f32_16x16x32_bf16 v[48:51], v[80:83], v[68:71], v[48:51]
	ds_read_b128 v[68:71], v84 offset:34816
	s_waitcnt lgkmcnt(0)
	v_mfma_f32_16x16x32_bf16 v[44:47], v[64:67], v[68:71], v[44:47]
	v_mfma_f32_16x16x32_bf16 v[40:43], v[72:75], v[68:71], v[40:43]
	v_mfma_f32_16x16x32_bf16 v[36:39], v[76:79], v[68:71], v[36:39]
	v_mfma_f32_16x16x32_bf16 v[32:35], v[80:83], v[68:71], v[32:35]
	ds_read_b128 v[68:71], v84 offset:36864
	s_waitcnt lgkmcnt(0)
	v_mfma_f32_16x16x32_bf16 v[28:31], v[64:67], v[68:71], v[28:31]
	v_mfma_f32_16x16x32_bf16 v[24:27], v[72:75], v[68:71], v[24:27]
	v_mfma_f32_16x16x32_bf16 v[20:23], v[76:79], v[68:71], v[20:23]
	v_mfma_f32_16x16x32_bf16 v[16:19], v[80:83], v[68:71], v[16:19]
	ds_read_b128 v[68:71], v84 offset:38912
	s_waitcnt lgkmcnt(0)
	v_mfma_f32_16x16x32_bf16 v[12:15], v[64:67], v[68:71], v[12:15]
	v_mfma_f32_16x16x32_bf16 v[8:11], v[72:75], v[68:71], v[8:11]
	v_mfma_f32_16x16x32_bf16 v[4:7], v[76:79], v[68:71], v[4:7]
	v_mfma_f32_16x16x32_bf16 v[0:3], v[80:83], v[68:71], v[0:3]
	v_mov_b32_e32 v64, v111
	s_barrier
	s_cmp_gt_i32 s16, 15
	v_ashrrev_i32_e32 v68, 7, v64
	v_bfe_u32 v70, v64, 6, 1
	v_and_b32_e32 v71, 15, v64
	v_bfe_u32 v69, v64, 4, 2
	s_mov_b64 s[18:19], -1
	s_cbranch_scc0 .LBB0_1046
	s_add_i32 s20, s20, -16
	s_cmp_eq_u32 s20, 0
	s_mov_b64 s[18:19], s[2:3]
	s_cbranch_scc1 .LBB0_1045
	s_lshr_b32 s11, s20, 3
	s_add_i32 s11, s11, -1
	s_mul_hi_u32 s17, s11, 0x4800000
	s_mul_i32 s11, s11, 0x4800000
	s_add_u32 s18, s27, s11
	s_addc_u32 s19, s28, s17

	.amdhsa_kernel _Z11mega_kernel6Params
		.amdhsa_group_segment_fixed_size 66048
		.amdhsa_private_segment_fixed_size 0
		.amdhsa_kernarg_size 512
		.amdhsa_user_sgpr_count 2
		.amdhsa_user_sgpr_dispatch_ptr 0
		.amdhsa_user_sgpr_queue_ptr 0
		.amdhsa_user_sgpr_kernarg_segment_ptr 1
		.amdhsa_user_sgpr_dispatch_id 0
		.amdhsa_user_sgpr_kernarg_preload_length 0
		.amdhsa_user_sgpr_kernarg_preload_offset 0
		.amdhsa_user_sgpr_private_segment_size 0
		.amdhsa_uses_dynamic_stack 0
		.amdhsa_enable_private_segment 0
		.amdhsa_system_sgpr_workgroup_id_x 1
		.amdhsa_system_sgpr_workgroup_id_y 0
		.amdhsa_system_sgpr_workgroup_id_z 0
		.amdhsa_system_sgpr_workgroup_info 0
		.amdhsa_system_vgpr_workitem_id 2
		.amdhsa_next_free_vgpr 256
		.amdhsa_next_free_sgpr 102
		.amdhsa_accum_offset 256
		.amdhsa_reserve_vcc 1
		.amdhsa_float_round_mode_32 0
		.amdhsa_float_round_mode_16_64 0
		.amdhsa_float_denorm_mode_32 3
		.amdhsa_float_denorm_mode_16_64 3
		.amdhsa_dx10_clamp 1
		.amdhsa_ieee_mode 1
		.amdhsa_fp16_overflow 0
		.amdhsa_tg_split 0
		.amdhsa_exception_fp_ieee_invalid_op 0
		.amdhsa_exception_fp_denorm_src 0
		.amdhsa_exception_fp_ieee_div_zero 0
		.amdhsa_exception_fp_ieee_overflow 0
		.amdhsa_exception_fp_ieee_underflow 0
		.amdhsa_exception_fp_ieee_inexact 0
		.amdhsa_exception_int_div_zero 0
	.end_amdhsa_kernel

amdhsa.kernels:
  - .agpr_count:     0
    .args:
      - .offset:         0
        .size:           256
        .value_kind:     by_value
      - .offset:         256
        .size:           4
        .value_kind:     hidden_block_count_x
      - .offset:         260
        .size:           4
        .value_kind:     hidden_block_count_y
      - .offset:         264
        .size:           4
        .value_kind:     hidden_block_count_z
      - .offset:         268
        .size:           2
        .value_kind:     hidden_group_size_x
      - .offset:         270
        .size:           2
        .value_kind:     hidden_group_size_y
      - .offset:         272
        .size:           2
        .value_kind:     hidden_group_size_z
      - .offset:         274
        .size:           2
        .value_kind:     hidden_remainder_x
      - .offset:         276
        .size:           2
        .value_kind:     hidden_remainder_y
      - .offset:         278
        .size:           2
        .value_kind:     hidden_remainder_z
      - .offset:         296
        .size:           8
        .value_kind:     hidden_global_offset_x
      - .offset:         304
        .size:           8
        .value_kind:     hidden_global_offset_y
      - .offset:         312
        .size:           8
        .value_kind:     hidden_global_offset_z
      - .offset:         320
        .size:           2
        .value_kind:     hidden_grid_dims
      - .offset:         344
        .size:           8
        .value_kind:     hidden_multigrid_sync_arg
    .group_segment_fixed_size: 66048
    .kernarg_segment_align: 8
    .kernarg_segment_size: 512
    .language:       OpenCL C
    .language_version:
      - 2
      - 0
    .max_flat_workgroup_size: 256
    .name:           _Z11mega_kernel6Params
    .private_segment_fixed_size: 0
    .sgpr_count:     108
    .sgpr_spill_count: 134
    .symbol:         _Z11mega_kernel6Params.kd
    .uniform_work_group_size: 1
    .uses_dynamic_stack: false
    .vgpr_count:     256
    .vgpr_spill_count: 0
    .wavefront_size: 64
